# P4 GEMM first K-iteration peeled as well (C=0 first MFMAs, no accumulator zeroing), 4-byte pad keeps downstream code phase
# baseline (speedup 1.0000x reference)
.LBB0_613:
	s_ashr_i32 s17, s16, 31
	v_cmp_lt_i64_e32 vcc, s[18:19], v[154:155]
	s_lshl_b64 s[18:19], s[16:17], 19
	s_add_u32 s18, s78, s18
	s_addc_u32 s19, s79, s19
	s_and_b64 s[20:21], vcc, exec
	s_cselect_b32 s17, s19, s25
	s_cselect_b32 s23, s18, s24
	s_ashr_i32 s15, s14, 31
	s_lshl_b64 s[20:21], s[14:15], 19
	s_add_u32 s20, s44, s20
	s_addc_u32 s21, s45, s21
	s_and_b64 s[28:29], vcc, exec
	s_cselect_b32 s15, s21, s27
	s_cselect_b32 s57, s20, s26
	s_add_u32 s24, s24, 0x40080
	s_addc_u32 s25, s25, 0
	s_add_u32 s58, s26, 0x100
	s_addc_u32 s59, s27, 0
	s_mov_b32 s60, -2
	s_nop 0
	ds_read_b128 v[128:131], v164
	ds_read_b128 v[132:135], v164 offset:1024
	ds_read_b128 v[136:139], v164 offset:2048
	ds_read_b128 v[140:143], v164 offset:3072
	s_add_u32 s26, s24, 0xfffc0080
	s_addc_u32 s27, s25, -1
	s_cmp_eq_u32 s60, 12
	s_cselect_b32 s29, s17, s27
	s_cselect_b32 s28, s23, s26
	s_cselect_b32 s27, s15, s59
	s_cselect_b32 s26, s57, s58
	v_lshl_add_u64 v[196:197], s[24:25], 0, v[150:151]
	s_add_i32 m0, s36, 0xc000
	ds_read_b128 v[158:161], v165
	ds_read_b128 v[168:171], v165 offset:1024
	ds_read_b128 v[172:175], v165 offset:2048
	ds_read_b128 v[176:179], v165 offset:3072
	ds_read_b128 v[180:183], v165 offset:4096
	ds_read_b128 v[184:187], v165 offset:5120
	ds_read_b128 v[188:191], v165 offset:6144
	ds_read_b128 v[192:195], v165 offset:7168
	global_load_lds_dwordx4 v[196:197], off
	v_lshl_add_u64 v[196:197], s[24:25], 0, v[152:153]
	s_add_i32 m0, s36, 0xe000
	s_nop 0
	global_load_lds_dwordx4 v[196:197], off
	s_waitcnt lgkmcnt(8)
	s_barrier
	s_waitcnt lgkmcnt(0)
	s_waitcnt lgkmcnt(0)
	v_mfma_f32_16x16x32_bf16 v[124:127], v[128:131], v[158:161], 0
	v_mfma_f32_16x16x32_bf16 v[120:123], v[136:139], v[158:161], 0
	v_mfma_f32_16x16x32_bf16 v[116:119], v[128:131], v[172:175], 0
	v_mfma_f32_16x16x32_bf16 v[112:115], v[136:139], v[172:175], 0
	v_mfma_f32_16x16x32_bf16 v[104:107], v[128:131], v[180:183], 0
	v_mfma_f32_16x16x32_bf16 v[96:99], v[136:139], v[180:183], 0
	v_mfma_f32_16x16x32_bf16 v[92:95], v[128:131], v[188:191], 0
	v_mfma_f32_16x16x32_bf16 v[76:79], v[136:139], v[188:191], 0
	v_mfma_f32_16x16x32_bf16 v[124:127], v[132:135], v[168:171], v[124:127]
	v_mfma_f32_16x16x32_bf16 v[120:123], v[140:143], v[168:171], v[120:123]
	v_mfma_f32_16x16x32_bf16 v[116:119], v[132:135], v[176:179], v[116:119]
	v_mfma_f32_16x16x32_bf16 v[112:115], v[140:143], v[176:179], v[112:115]
	v_mfma_f32_16x16x32_bf16 v[104:107], v[132:135], v[184:187], v[104:107]
	v_mfma_f32_16x16x32_bf16 v[96:99], v[140:143], v[184:187], v[96:99]
	v_mfma_f32_16x16x32_bf16 v[92:95], v[132:135], v[192:195], v[92:95]
	v_mfma_f32_16x16x32_bf16 v[76:79], v[140:143], v[192:195], v[76:79]
	s_barrier
	s_add_i32 s61, s48, s35
	v_lshl_add_u64 v[212:213], s[26:27], 0, v[144:145]
	s_mov_b32 m0, s61
	ds_read_b128 v[196:199], v166
	ds_read_b128 v[200:203], v166 offset:1024
	ds_read_b128 v[204:207], v166 offset:2048
	ds_read_b128 v[208:211], v166 offset:3072
	global_load_lds_dwordx4 v[212:213], off
	v_lshl_add_u64 v[214:215], s[26:27], 0, v[146:147]
	s_add_i32 m0, s61, 0x2000
	s_nop 0
	global_load_lds_dwordx4 v[214:215], off
	s_barrier
	s_waitcnt lgkmcnt(0)
	s_waitcnt lgkmcnt(0)
	v_mfma_f32_16x16x32_bf16 v[108:111], v[196:199], v[158:161], 0
	v_mfma_f32_16x16x32_bf16 v[100:103], v[204:207], v[158:161], 0
	v_mfma_f32_16x16x32_bf16 v[88:91], v[196:199], v[172:175], 0
	v_mfma_f32_16x16x32_bf16 v[84:87], v[204:207], v[172:175], 0
	v_mfma_f32_16x16x32_bf16 v[80:83], v[196:199], v[180:183], 0
	v_mfma_f32_16x16x32_bf16 v[72:75], v[204:207], v[180:183], 0
	v_mfma_f32_16x16x32_bf16 v[68:71], v[196:199], v[188:191], 0
	v_mfma_f32_16x16x32_bf16 v[64:67], v[204:207], v[188:191], 0
	v_mfma_f32_16x16x32_bf16 v[108:111], v[200:203], v[168:171], v[108:111]
	v_mfma_f32_16x16x32_bf16 v[100:103], v[208:211], v[168:171], v[100:103]
	v_mfma_f32_16x16x32_bf16 v[88:91], v[200:203], v[176:179], v[88:91]
	v_mfma_f32_16x16x32_bf16 v[84:87], v[208:211], v[176:179], v[84:87]
	v_mfma_f32_16x16x32_bf16 v[80:83], v[200:203], v[184:187], v[80:83]
	v_mfma_f32_16x16x32_bf16 v[72:75], v[208:211], v[184:187], v[72:75]
	v_mfma_f32_16x16x32_bf16 v[68:71], v[200:203], v[192:195], v[68:71]
	v_mfma_f32_16x16x32_bf16 v[64:67], v[208:211], v[192:195], v[64:67]
	s_mov_b32 m0, s36
	v_lshl_add_u64 v[216:217], s[28:29], 0, v[144:145]
	s_barrier
	ds_read_b128 v[158:161], v165 offset:16384
	ds_read_b128 v[168:171], v165 offset:17408
	ds_read_b128 v[172:175], v165 offset:18432
	ds_read_b128 v[176:179], v165 offset:19456
	ds_read_b128 v[180:183], v165 offset:20480
	ds_read_b128 v[184:187], v165 offset:21504
	ds_read_b128 v[188:191], v165 offset:22528
	ds_read_b128 v[192:195], v165 offset:23552
	global_load_lds_dwordx4 v[216:217], off
	v_lshl_add_u64 v[218:219], s[28:29], 0, v[146:147]
	s_mov_b32 m0, s37
	s_nop 0
	global_load_lds_dwordx4 v[218:219], off
	s_barrier
	s_waitcnt lgkmcnt(0)
	s_waitcnt lgkmcnt(0)
	v_mfma_f32_16x16x32_bf16 v[60:63], v[128:131], v[158:161], 0
	v_mfma_f32_16x16x32_bf16 v[56:59], v[136:139], v[158:161], 0
	v_mfma_f32_16x16x32_bf16 v[52:55], v[128:131], v[172:175], 0
	v_mfma_f32_16x16x32_bf16 v[48:51], v[136:139], v[172:175], 0
	v_mfma_f32_16x16x32_bf16 v[44:47], v[128:131], v[180:183], 0
	v_mfma_f32_16x16x32_bf16 v[24:27], v[136:139], v[180:183], 0
	v_mfma_f32_16x16x32_bf16 v[20:23], v[128:131], v[188:191], 0
	v_mfma_f32_16x16x32_bf16 v[8:11], v[136:139], v[188:191], 0
	v_mfma_f32_16x16x32_bf16 v[60:63], v[132:135], v[168:171], v[60:63]
	v_mfma_f32_16x16x32_bf16 v[56:59], v[140:143], v[168:171], v[56:59]
	v_mfma_f32_16x16x32_bf16 v[52:55], v[132:135], v[176:179], v[52:55]
	v_mfma_f32_16x16x32_bf16 v[48:51], v[140:143], v[176:179], v[48:51]
	v_mfma_f32_16x16x32_bf16 v[44:47], v[132:135], v[184:187], v[44:47]
	v_mfma_f32_16x16x32_bf16 v[24:27], v[140:143], v[184:187], v[24:27]
	v_mfma_f32_16x16x32_bf16 v[20:23], v[132:135], v[192:195], v[20:23]
	v_mfma_f32_16x16x32_bf16 v[8:11], v[140:143], v[192:195], v[8:11]
	s_barrier
	s_add_u32 s62, s26, 0x40000
	s_addc_u32 s63, s27, 0
	s_add_i32 s61, s49, s35
	v_lshl_add_u64 v[128:129], s[62:63], 0, v[144:145]
	s_mov_b32 m0, s61
	s_nop 0
	global_load_lds_dwordx4 v[128:129], off
	v_lshl_add_u64 v[128:129], s[62:63], 0, v[146:147]
	s_add_i32 m0, s61, 0x2000
	s_nop 0
	global_load_lds_dwordx4 v[128:129], off
	s_waitcnt vmcnt(6)
	s_barrier
	v_mfma_f32_16x16x32_bf16 v[40:43], v[196:199], v[158:161], 0
	v_mfma_f32_16x16x32_bf16 v[36:39], v[204:207], v[158:161], 0
	v_mfma_f32_16x16x32_bf16 v[32:35], v[196:199], v[172:175], 0
	v_mfma_f32_16x16x32_bf16 v[28:31], v[204:207], v[172:175], 0
	v_mfma_f32_16x16x32_bf16 v[16:19], v[196:199], v[180:183], 0
	v_mfma_f32_16x16x32_bf16 v[12:15], v[204:207], v[180:183], 0
	v_mfma_f32_16x16x32_bf16 v[4:7], v[196:199], v[188:191], 0
	v_mfma_f32_16x16x32_bf16 v[0:3], v[204:207], v[188:191], 0
	v_mfma_f32_16x16x32_bf16 v[40:43], v[200:203], v[168:171], v[40:43]
	v_mfma_f32_16x16x32_bf16 v[36:39], v[208:211], v[168:171], v[36:39]
	v_mfma_f32_16x16x32_bf16 v[32:35], v[200:203], v[176:179], v[32:35]
	v_mfma_f32_16x16x32_bf16 v[28:31], v[208:211], v[176:179], v[28:31]
	v_mfma_f32_16x16x32_bf16 v[16:19], v[200:203], v[184:187], v[16:19]
	v_mfma_f32_16x16x32_bf16 v[12:15], v[208:211], v[184:187], v[12:15]
	v_mfma_f32_16x16x32_bf16 v[4:7], v[200:203], v[192:195], v[4:7]
	v_mfma_f32_16x16x32_bf16 v[0:3], v[208:211], v[192:195], v[0:3]
	s_add_i32 s61, 0, 0x18000
	v_add_u32_e32 v140, s61, v162
	s_barrier
	ds_read_b128 v[128:131], v140
	ds_read_b128 v[132:135], v140 offset:1024
	ds_read_b128 v[136:139], v140 offset:2048
	ds_read_b128 v[140:143], v140 offset:3072
	s_add_u32 s28, s28, 0x40000
	s_addc_u32 s29, s29, 0
	s_mov_b32 m0, s40
	v_lshl_add_u64 v[196:197], s[28:29], 0, v[144:145]
	ds_read_b128 v[158:161], v165 offset:32768
	ds_read_b128 v[168:171], v165 offset:33792
	ds_read_b128 v[172:175], v165 offset:34816
	ds_read_b128 v[176:179], v165 offset:35840
	ds_read_b128 v[180:183], v165 offset:36864
	ds_read_b128 v[184:187], v165 offset:37888
	ds_read_b128 v[188:191], v165 offset:38912
	ds_read_b128 v[192:195], v165 offset:39936
	global_load_lds_dwordx4 v[196:197], off
	v_lshl_add_u64 v[196:197], s[28:29], 0, v[146:147]
	s_mov_b32 m0, s41
	s_nop 0
	global_load_lds_dwordx4 v[196:197], off
	s_waitcnt lgkmcnt(8)
	s_barrier
	s_waitcnt lgkmcnt(0)
	s_waitcnt lgkmcnt(0)
	v_mfma_f32_16x16x32_bf16 v[124:127], v[128:131], v[158:161], v[124:127]
	v_mfma_f32_16x16x32_bf16 v[120:123], v[136:139], v[158:161], v[120:123]
	v_mfma_f32_16x16x32_bf16 v[116:119], v[128:131], v[172:175], v[116:119]
	v_mfma_f32_16x16x32_bf16 v[112:115], v[136:139], v[172:175], v[112:115]
	v_mfma_f32_16x16x32_bf16 v[104:107], v[128:131], v[180:183], v[104:107]
	v_mfma_f32_16x16x32_bf16 v[96:99], v[136:139], v[180:183], v[96:99]
	v_mfma_f32_16x16x32_bf16 v[92:95], v[128:131], v[188:191], v[92:95]
	v_mfma_f32_16x16x32_bf16 v[76:79], v[136:139], v[188:191], v[76:79]
	v_mfma_f32_16x16x32_bf16 v[124:127], v[132:135], v[168:171], v[124:127]
	v_mfma_f32_16x16x32_bf16 v[120:123], v[140:143], v[168:171], v[120:123]
	v_mfma_f32_16x16x32_bf16 v[116:119], v[132:135], v[176:179], v[116:119]
	v_mfma_f32_16x16x32_bf16 v[112:115], v[140:143], v[176:179], v[112:115]
	v_mfma_f32_16x16x32_bf16 v[104:107], v[132:135], v[184:187], v[104:107]
	v_mfma_f32_16x16x32_bf16 v[96:99], v[140:143], v[184:187], v[96:99]
	v_mfma_f32_16x16x32_bf16 v[92:95], v[132:135], v[192:195], v[92:95]
	v_mfma_f32_16x16x32_bf16 v[76:79], v[140:143], v[192:195], v[76:79]
	s_barrier
	s_add_i32 s28, 0, 0x1c000
	s_add_i32 s29, s61, s35
	v_add_u32_e32 v167, s28, v162
	v_lshl_add_u64 v[212:213], v[212:213], 0, s[4:5]
	s_mov_b32 m0, s29
	ds_read_b128 v[196:199], v167
	ds_read_b128 v[200:203], v167 offset:1024
	ds_read_b128 v[204:207], v167 offset:2048
	ds_read_b128 v[208:211], v167 offset:3072
	global_load_lds_dwordx4 v[212:213], off
	v_lshl_add_u64 v[212:213], v[214:215], 0, s[4:5]
	s_add_i32 m0, s29, 0x2000
	s_nop 0
	global_load_lds_dwordx4 v[212:213], off
	s_barrier
	s_waitcnt lgkmcnt(0)
	s_waitcnt lgkmcnt(0)
	v_mfma_f32_16x16x32_bf16 v[108:111], v[196:199], v[158:161], v[108:111]
	v_mfma_f32_16x16x32_bf16 v[100:103], v[204:207], v[158:161], v[100:103]
	v_mfma_f32_16x16x32_bf16 v[88:91], v[196:199], v[172:175], v[88:91]
	v_mfma_f32_16x16x32_bf16 v[84:87], v[204:207], v[172:175], v[84:87]
	v_mfma_f32_16x16x32_bf16 v[80:83], v[196:199], v[180:183], v[80:83]
	v_mfma_f32_16x16x32_bf16 v[72:75], v[204:207], v[180:183], v[72:75]
	v_mfma_f32_16x16x32_bf16 v[68:71], v[196:199], v[188:191], v[68:71]
	v_mfma_f32_16x16x32_bf16 v[64:67], v[204:207], v[188:191], v[64:67]
	v_mfma_f32_16x16x32_bf16 v[108:111], v[200:203], v[168:171], v[108:111]
	v_mfma_f32_16x16x32_bf16 v[100:103], v[208:211], v[168:171], v[100:103]
	v_mfma_f32_16x16x32_bf16 v[88:91], v[200:203], v[176:179], v[88:91]
	v_mfma_f32_16x16x32_bf16 v[84:87], v[208:211], v[176:179], v[84:87]
	v_mfma_f32_16x16x32_bf16 v[80:83], v[200:203], v[184:187], v[80:83]
	v_mfma_f32_16x16x32_bf16 v[72:75], v[208:211], v[184:187], v[72:75]
	v_mfma_f32_16x16x32_bf16 v[68:71], v[200:203], v[192:195], v[68:71]
	v_mfma_f32_16x16x32_bf16 v[64:67], v[208:211], v[192:195], v[64:67]
	s_mov_b32 m0, s43
	v_lshl_add_u64 v[212:213], v[216:217], 0, s[4:5]
	s_barrier
	ds_read_b128 v[158:161], v165 offset:49152
	ds_read_b128 v[168:171], v165 offset:50176
	ds_read_b128 v[172:175], v165 offset:51200
	ds_read_b128 v[176:179], v165 offset:52224
	ds_read_b128 v[180:183], v165 offset:53248
	ds_read_b128 v[184:187], v165 offset:54272
	ds_read_b128 v[188:191], v165 offset:55296
	ds_read_b128 v[192:195], v165 offset:56320
	global_load_lds_dwordx4 v[212:213], off
	v_lshl_add_u64 v[212:213], v[218:219], 0, s[4:5]
	s_mov_b32 m0, s46
	s_nop 0
	global_load_lds_dwordx4 v[212:213], off
	s_barrier
	s_waitcnt lgkmcnt(0)
	s_waitcnt lgkmcnt(0)
	v_mfma_f32_16x16x32_bf16 v[60:63], v[128:131], v[158:161], v[60:63]
	v_mfma_f32_16x16x32_bf16 v[56:59], v[136:139], v[158:161], v[56:59]
	v_mfma_f32_16x16x32_bf16 v[52:55], v[128:131], v[172:175], v[52:55]
	v_mfma_f32_16x16x32_bf16 v[48:51], v[136:139], v[172:175], v[48:51]
	v_mfma_f32_16x16x32_bf16 v[44:47], v[128:131], v[180:183], v[44:47]
	v_mfma_f32_16x16x32_bf16 v[24:27], v[136:139], v[180:183], v[24:27]
	v_mfma_f32_16x16x32_bf16 v[20:23], v[128:131], v[188:191], v[20:23]
	v_mfma_f32_16x16x32_bf16 v[8:11], v[136:139], v[188:191], v[8:11]
	v_mfma_f32_16x16x32_bf16 v[60:63], v[132:135], v[168:171], v[60:63]
	v_mfma_f32_16x16x32_bf16 v[56:59], v[140:143], v[168:171], v[56:59]
	v_mfma_f32_16x16x32_bf16 v[52:55], v[132:135], v[176:179], v[52:55]
	v_mfma_f32_16x16x32_bf16 v[48:51], v[140:143], v[176:179], v[48:51]
	v_mfma_f32_16x16x32_bf16 v[44:47], v[132:135], v[184:187], v[44:47]
	v_mfma_f32_16x16x32_bf16 v[24:27], v[140:143], v[184:187], v[24:27]
	v_mfma_f32_16x16x32_bf16 v[20:23], v[132:135], v[192:195], v[20:23]
	v_mfma_f32_16x16x32_bf16 v[8:11], v[140:143], v[192:195], v[8:11]
	s_barrier
	s_add_u32 s26, s26, 0x40080
	s_addc_u32 s27, s27, 0
	s_add_i32 s28, s28, s35
	v_lshl_add_u64 v[128:129], s[26:27], 0, v[144:145]
	s_mov_b32 m0, s28
	s_nop 0
	global_load_lds_dwordx4 v[128:129], off
	v_lshl_add_u64 v[128:129], s[26:27], 0, v[146:147]
	s_add_i32 m0, s28, 0x2000
	s_nop 0
	global_load_lds_dwordx4 v[128:129], off
	s_waitcnt vmcnt(6)
	s_barrier
	v_mfma_f32_16x16x32_bf16 v[40:43], v[196:199], v[158:161], v[40:43]
	v_mfma_f32_16x16x32_bf16 v[36:39], v[204:207], v[158:161], v[36:39]
	v_mfma_f32_16x16x32_bf16 v[32:35], v[196:199], v[172:175], v[32:35]
	v_mfma_f32_16x16x32_bf16 v[28:31], v[204:207], v[172:175], v[28:31]
	v_mfma_f32_16x16x32_bf16 v[16:19], v[196:199], v[180:183], v[16:19]
	v_mfma_f32_16x16x32_bf16 v[12:15], v[204:207], v[180:183], v[12:15]
	v_mfma_f32_16x16x32_bf16 v[4:7], v[196:199], v[188:191], v[4:7]
	v_mfma_f32_16x16x32_bf16 v[0:3], v[204:207], v[188:191], v[0:3]
	v_mfma_f32_16x16x32_bf16 v[40:43], v[200:203], v[168:171], v[40:43]
	v_mfma_f32_16x16x32_bf16 v[36:39], v[208:211], v[168:171], v[36:39]
	v_mfma_f32_16x16x32_bf16 v[32:35], v[200:203], v[176:179], v[32:35]
	v_mfma_f32_16x16x32_bf16 v[28:31], v[208:211], v[176:179], v[28:31]
	v_mfma_f32_16x16x32_bf16 v[16:19], v[200:203], v[184:187], v[16:19]
	v_mfma_f32_16x16x32_bf16 v[12:15], v[208:211], v[184:187], v[12:15]
	v_mfma_f32_16x16x32_bf16 v[4:7], v[200:203], v[192:195], v[4:7]
	v_mfma_f32_16x16x32_bf16 v[0:3], v[208:211], v[192:195], v[0:3]
	s_add_i32 s60, s60, 2
	s_add_u32 s24, s24, 0x100
	s_addc_u32 s25, s25, 0
	s_add_u32 s58, s58, 0x100
	s_addc_u32 s59, s59, 0
	s_cmp_gt_u32 s60, 13
	s_barrier
